# GEMM K-loops incl. half-tile loops: M0 via s_add_i32 from a wave-base SGPR (no v_readfirstlane + s_mov per DMA piece)
# speedup vs baseline: 1.0150x; 1.0074x over previous
.LBB0_107:
	s_or_b64 exec, exec, s[72:73]
	v_mov_b32_e32 v3, v1
	s_waitcnt vmcnt(8)
	v_lshl_add_u64 v[14:15], s[0:1], 0, v[2:3]
	v_lshl_add_u64 v[18:19], s[12:13], 0, v[2:3]
	v_lshl_add_u64 v[22:23], s[14:15], 0, v[2:3]
	v_lshl_add_u64 v[66:67], s[16:17], 0, v[2:3]
	v_and_b32_e32 v84, 15, v82
	v_bfe_u32 v86, v82, 4, 2
	v_lshlrev_b32_e32 v3, 2, v82
	v_add_u32_e32 v95, 0x18000, v87
	v_lshl_add_u64 v[12:13], s[0:1], 0, v[0:1]
	v_lshl_add_u64 v[16:17], s[12:13], 0, v[0:1]
	v_lshl_add_u64 v[20:21], s[14:15], 0, v[0:1]
	v_lshl_add_u64 v[68:69], s[16:17], 0, v[0:1]
	v_lshlrev_b32_e32 v0, 6, v84
	v_lshlrev_b32_e32 v2, 4, v86
	v_and_b32_e32 v3, 32, v3
	s_mov_b64 s[12:13], 0x80
	v_readfirstlane_b32 s1, v95
	v_add_u32_e32 v96, 0x1a000, v87
	v_bitop3_b32 v24, v2, v3, v0 bitop3:0x36
	v_lshl_add_u64 v[2:3], v[12:13], 0, s[12:13]
	s_mov_b32 m0, s1
	v_readfirstlane_b32 s1, v96
	v_add_u32_e32 v97, 0x8000, v87
	s_waitcnt vmcnt(4)
	s_barrier
	global_load_lds_dwordx4 v[2:3], off
	v_lshl_add_u64 v[2:3], v[14:15], 0, s[12:13]
	s_mov_b32 m0, s1
	v_readfirstlane_b32 s1, v97
	v_add_u32_e32 v98, 0xa000, v87
	global_load_lds_dwordx4 v[2:3], off
	v_lshl_add_u64 v[2:3], v[16:17], 0, s[12:13]
	s_mov_b32 m0, s1
	v_readfirstlane_b32 s1, v98
	v_add_u32_e32 v100, 0x1c000, v87
	global_load_lds_dwordx4 v[2:3], off
	v_lshl_add_u64 v[2:3], v[18:19], 0, s[12:13]
	s_mov_b32 m0, s1
	v_readfirstlane_b32 s1, v100
	v_add_u32_e32 v101, 0x1e000, v87
	global_load_lds_dwordx4 v[2:3], off
	v_lshl_add_u64 v[2:3], v[20:21], 0, s[12:13]
	s_mov_b32 m0, s1
	v_readfirstlane_b32 s1, v101
	global_load_lds_dwordx4 v[2:3], off
	v_lshl_add_u64 v[2:3], v[22:23], 0, s[12:13]
	s_mov_b32 m0, s1
	s_sub_i32 s5, s56, s54
	global_load_lds_dwordx4 v[2:3], off
	s_sub_i32 s5, s5, s77
	s_sext_i32_i16 s5, s5
	s_lshl_b32 s1, s76, 10
	s_lshl_b32 s5, s5, 8
	s_and_b32 s0, s52, 0x80
	s_add_i32 s1, s1, s5
	s_or_b32 s0, s0, s1
	s_ashr_i32 s1, s0, 31
	s_lshl_b64 s[12:13], s[0:1], 12
	s_add_u32 s12, s57, s12
	v_readlane_b32 s36, v253, 33
	s_addc_u32 s13, s63, s13
	v_readlane_b32 s48, v253, 45
	v_readlane_b32 s49, v253, 46
	s_add_u32 s10, s48, s10
	v_lshlrev_b32_e32 v2, 14, v7
	s_addc_u32 s11, s49, s11
	s_addk_i32 s0, 0x80
	v_lshlrev_b32_e32 v0, 14, v4
	v_and_b32_e32 v2, 0x7fff8000, v2
	s_ashr_i32 s1, s0, 31
	v_and_b32_e32 v0, 0x7fff8000, v0
	v_lshl_add_u32 v2, v9, 11, v2
	s_lshl_b64 s[0:1], s[0:1], 12
	v_lshl_add_u32 v0, v5, 11, v0
	v_or_b32_e32 v2, v2, v10
	s_add_u32 s0, s57, s0
	v_bfe_u32 v85, v82, 6, 2
	s_waitcnt vmcnt(6)
	v_or_b32_e32 v0, v0, v6
	v_add_lshl_u32 v2, v2, v11, 1
	v_mov_b32_e32 v3, v1
	s_addc_u32 s1, s63, s1
	v_lshlrev_b32_e32 v25, 13, v83
	v_lshl_or_b32 v26, v85, 12, v212
	v_add_lshl_u32 v0, v0, v8, 1
	v_lshl_add_u64 v[72:73], s[12:13], 0, v[2:3]
	v_lshl_add_u64 v[76:77], s[10:11], 0, v[2:3]
	v_lshl_add_u64 v[80:81], s[0:1], 0, v[2:3]
	v_mov_b32_e32 v2, 0
	v_lshl_add_u64 v[70:71], s[12:13], 0, v[0:1]
	v_lshl_add_u64 v[74:75], s[10:11], 0, v[0:1]
	v_lshl_add_u64 v[78:79], s[0:1], 0, v[0:1]
	s_mov_b32 s0, -2
	s_mov_b64 s[10:11], 0
	v_add_u32_e32 v99, v26, v24
	v_add_u32_e32 v0, v25, v24
	v_mov_b32_e32 v3, v2
	v_mov_b32_e32 v4, v2
	v_mov_b32_e32 v5, v2
	v_mov_b32_e32 v6, v2
	v_mov_b32_e32 v7, v2
	v_mov_b32_e32 v8, v2
	v_mov_b32_e32 v9, v2
	v_mov_b32_e32 v10, v2
	v_mov_b32_e32 v11, v2
	v_mov_b32_e32 v12, v2
	v_mov_b32_e32 v13, v2
	v_mov_b32_e32 v14, v2
	v_mov_b32_e32 v15, v2
	v_mov_b32_e32 v16, v2
	v_mov_b32_e32 v17, v2
	v_mov_b32_e32 v18, v2
	v_mov_b32_e32 v19, v2
	v_mov_b32_e32 v20, v2
	v_mov_b32_e32 v21, v2
	v_mov_b32_e32 v22, v2
	v_mov_b32_e32 v23, v2
	v_mov_b32_e32 v24, v2
	v_mov_b32_e32 v25, v2
	v_mov_b32_e32 v26, v2
	v_mov_b32_e32 v27, v2
	v_mov_b32_e32 v28, v2
	v_mov_b32_e32 v29, v2
	v_mov_b32_e32 v34, v2
	v_mov_b32_e32 v35, v2
	v_mov_b32_e32 v36, v2
	v_mov_b32_e32 v37, v2
	v_mov_b32_e32 v38, v2
	v_mov_b32_e32 v39, v2
	v_mov_b32_e32 v40, v2
	v_mov_b32_e32 v41, v2
	v_mov_b32_e32 v42, v2
	v_mov_b32_e32 v43, v2
	v_mov_b32_e32 v44, v2
	v_mov_b32_e32 v45, v2
	v_mov_b32_e32 v46, v2
	v_mov_b32_e32 v47, v2
	v_mov_b32_e32 v48, v2
	v_mov_b32_e32 v49, v2
	v_mov_b32_e32 v50, v2
	v_mov_b32_e32 v51, v2
	v_mov_b32_e32 v52, v2
	v_mov_b32_e32 v53, v2
	v_mov_b32_e32 v54, v2
	v_mov_b32_e32 v55, v2
	v_mov_b32_e32 v56, v2
	v_mov_b32_e32 v57, v2
	v_mov_b32_e32 v58, v2
	v_mov_b32_e32 v59, v2
	v_mov_b32_e32 v60, v2
	v_mov_b32_e32 v61, v2
	v_mov_b32_e32 v62, v2
	v_mov_b32_e32 v63, v2
	v_mov_b32_e32 v64, v2
	v_mov_b32_e32 v65, v2
	v_mov_b32_e32 v30, v2
	v_mov_b32_e32 v31, v2
	v_mov_b32_e32 v32, v2
	v_mov_b32_e32 v33, v2
	s_barrier
	v_readlane_b32 s37, v253, 34
	v_readlane_b32 s38, v253, 35
	v_readlane_b32 s39, v253, 36
	v_readlane_b32 s40, v253, 37
	v_readlane_b32 s41, v253, 38
	v_readlane_b32 s42, v253, 39
	v_readlane_b32 s43, v253, 40
	v_readlane_b32 s44, v253, 41
	v_readlane_b32 s45, v253, 42
	v_readlane_b32 s46, v253, 43
	v_readlane_b32 s47, v253, 44
	v_readlane_b32 s50, v253, 47
	v_readlane_b32 s51, v253, 48
	v_readfirstlane_b32 s1, v87
	s_nop 1
.LBB0_108:
	ds_read_b128 v[104:107], v99
	ds_read_b128 v[108:111], v99 offset:1024
	ds_read_b128 v[112:115], v99 offset:2048
	ds_read_b128 v[116:119], v99 offset:3072
	v_add_u32_e32 v102, 0xc000, v87
	v_lshl_add_u64 v[152:153], v[74:75], 0, s[10:11]
	v_lshl_add_u64 v[154:155], v[152:153], 0, s[60:61]
	s_add_i32 m0, s1, 0xc000
	v_add_u32_e32 v103, 0xe000, v87
	ds_read_b128 v[120:123], v0
	ds_read_b128 v[124:127], v0 offset:1024
	ds_read_b128 v[128:131], v0 offset:2048
	ds_read_b128 v[132:135], v0 offset:3072
	ds_read_b128 v[136:139], v0 offset:4096
	ds_read_b128 v[140:143], v0 offset:5120
	ds_read_b128 v[144:147], v0 offset:6144
	ds_read_b128 v[148:151], v0 offset:7168
	global_load_lds_dwordx4 v[154:155], off
	v_lshl_add_u64 v[154:155], v[76:77], 0, s[10:11]
	v_lshl_add_u64 v[156:157], v[154:155], 0, s[60:61]
	s_add_i32 m0, s1, 0xe000
	s_nop 0
	global_load_lds_dwordx4 v[156:157], off
	s_waitcnt lgkmcnt(8)
	s_barrier
	s_waitcnt lgkmcnt(0)
	s_setprio 1
	s_waitcnt lgkmcnt(0)
	v_mfma_f32_16x16x32_bf16 v[62:65], v[104:107], v[120:123], v[62:65]
	v_mfma_f32_16x16x32_bf16 v[58:61], v[112:115], v[120:123], v[58:61]
	v_mfma_f32_16x16x32_bf16 v[54:57], v[104:107], v[128:131], v[54:57]
	v_mfma_f32_16x16x32_bf16 v[50:53], v[112:115], v[128:131], v[50:53]
	v_mfma_f32_16x16x32_bf16 v[46:49], v[104:107], v[136:139], v[46:49]
	v_mfma_f32_16x16x32_bf16 v[42:45], v[112:115], v[136:139], v[42:45]
	v_mfma_f32_16x16x32_bf16 v[38:41], v[104:107], v[144:147], v[38:41]
	v_mfma_f32_16x16x32_bf16 v[34:37], v[112:115], v[144:147], v[34:37]
	v_mfma_f32_16x16x32_bf16 v[62:65], v[108:111], v[124:127], v[62:65]
	v_mfma_f32_16x16x32_bf16 v[58:61], v[116:119], v[124:127], v[58:61]
	v_mfma_f32_16x16x32_bf16 v[54:57], v[108:111], v[132:135], v[54:57]
	v_mfma_f32_16x16x32_bf16 v[50:53], v[116:119], v[132:135], v[50:53]
	v_mfma_f32_16x16x32_bf16 v[46:49], v[108:111], v[140:143], v[46:49]
	v_mfma_f32_16x16x32_bf16 v[42:45], v[116:119], v[140:143], v[42:45]
	v_mfma_f32_16x16x32_bf16 v[38:41], v[108:111], v[148:151], v[38:41]
	v_mfma_f32_16x16x32_bf16 v[34:37], v[116:119], v[148:151], v[34:37]
	s_setprio 0
	s_barrier
	v_lshl_add_u64 v[156:157], v[70:71], 0, s[10:11]
	v_lshl_add_u64 v[120:121], v[156:157], 0, s[74:75]
	s_add_i32 m0, s1, 0x10000
	v_lshl_add_u64 v[158:159], v[72:73], 0, s[10:11]
	global_load_lds_dwordx4 v[120:121], off
	v_lshl_add_u64 v[120:121], v[158:159], 0, s[74:75]
	s_add_i32 m0, s1, 0x12000
	global_load_lds_dwordx4 v[120:121], off
	v_lshl_add_u64 v[160:161], v[152:153], 0, s[74:75]
	s_mov_b32 m0, s1
	s_barrier
	s_waitcnt lgkmcnt(0)
	s_barrier
	ds_read_b128 v[120:123], v0 offset:16384
	ds_read_b128 v[124:127], v0 offset:17408
	ds_read_b128 v[128:131], v0 offset:18432
	ds_read_b128 v[132:135], v0 offset:19456
	ds_read_b128 v[136:139], v0 offset:20480
	ds_read_b128 v[140:143], v0 offset:21504
	ds_read_b128 v[144:147], v0 offset:22528
	ds_read_b128 v[148:151], v0 offset:23552
	global_load_lds_dwordx4 v[160:161], off
	v_lshl_add_u64 v[160:161], v[154:155], 0, s[74:75]
	s_add_i32 m0, s1, 0x2000
	s_nop 0
	global_load_lds_dwordx4 v[160:161], off
	s_barrier
	s_waitcnt lgkmcnt(0)
	s_setprio 1
	s_waitcnt lgkmcnt(0)
	v_mfma_f32_16x16x32_bf16 v[2:5], v[104:107], v[120:123], v[2:5]
	v_mfma_f32_16x16x32_bf16 v[6:9], v[112:115], v[120:123], v[6:9]
	v_mfma_f32_16x16x32_bf16 v[10:13], v[104:107], v[128:131], v[10:13]
	v_mfma_f32_16x16x32_bf16 v[14:17], v[112:115], v[128:131], v[14:17]
	v_mfma_f32_16x16x32_bf16 v[18:21], v[104:107], v[136:139], v[18:21]
	v_mfma_f32_16x16x32_bf16 v[22:25], v[112:115], v[136:139], v[22:25]
	v_mfma_f32_16x16x32_bf16 v[26:29], v[104:107], v[144:147], v[26:29]
	v_mfma_f32_16x16x32_bf16 v[30:33], v[112:115], v[144:147], v[30:33]
	v_mfma_f32_16x16x32_bf16 v[2:5], v[108:111], v[124:127], v[2:5]
	v_mfma_f32_16x16x32_bf16 v[6:9], v[116:119], v[124:127], v[6:9]
	v_mfma_f32_16x16x32_bf16 v[10:13], v[108:111], v[132:135], v[10:13]
	v_mfma_f32_16x16x32_bf16 v[14:17], v[116:119], v[132:135], v[14:17]
	v_mfma_f32_16x16x32_bf16 v[18:21], v[108:111], v[140:143], v[18:21]
	v_mfma_f32_16x16x32_bf16 v[22:25], v[116:119], v[140:143], v[22:25]
	v_mfma_f32_16x16x32_bf16 v[26:29], v[108:111], v[148:151], v[26:29]
	v_mfma_f32_16x16x32_bf16 v[30:33], v[116:119], v[148:151], v[30:33]
	s_setprio 0
	s_barrier
	v_lshl_add_u64 v[160:161], v[78:79], 0, s[10:11]
	v_lshl_add_u64 v[104:105], v[160:161], 0, s[74:75]
	s_add_i32 m0, s1, 0x14000
	v_lshl_add_u64 v[162:163], v[80:81], 0, s[10:11]
	global_load_lds_dwordx4 v[104:105], off
	v_lshl_add_u64 v[104:105], v[162:163], 0, s[74:75]
	s_add_i32 m0, s1, 0x16000
	s_nop 0
	global_load_lds_dwordx4 v[104:105], off
	s_waitcnt vmcnt(6)
	s_barrier
	s_barrier
	ds_read_b128 v[104:107], v99 offset:32768
	ds_read_b128 v[108:111], v99 offset:33792
	ds_read_b128 v[112:115], v99 offset:34816
	ds_read_b128 v[116:119], v99 offset:35840
	v_lshl_add_u64 v[164:165], v[152:153], 0, s[18:19]
	s_add_i32 m0, s1, 0x4000
	ds_read_b128 v[120:123], v0 offset:32768
	ds_read_b128 v[124:127], v0 offset:33792
	ds_read_b128 v[128:131], v0 offset:34816
	ds_read_b128 v[132:135], v0 offset:35840
	ds_read_b128 v[136:139], v0 offset:36864
	ds_read_b128 v[140:143], v0 offset:37888
	ds_read_b128 v[144:147], v0 offset:38912
	ds_read_b128 v[148:151], v0 offset:39936
	global_load_lds_dwordx4 v[164:165], off
	v_lshl_add_u64 v[164:165], v[154:155], 0, s[18:19]
	s_add_i32 m0, s1, 0x6000
	s_nop 0
	global_load_lds_dwordx4 v[164:165], off
	s_waitcnt lgkmcnt(8)
	s_barrier
	s_waitcnt lgkmcnt(0)
	s_setprio 1
	s_waitcnt lgkmcnt(0)
	v_mfma_f32_16x16x32_bf16 v[62:65], v[104:107], v[120:123], v[62:65]
	v_mfma_f32_16x16x32_bf16 v[58:61], v[112:115], v[120:123], v[58:61]
	v_mfma_f32_16x16x32_bf16 v[54:57], v[104:107], v[128:131], v[54:57]
	v_mfma_f32_16x16x32_bf16 v[50:53], v[112:115], v[128:131], v[50:53]
	v_mfma_f32_16x16x32_bf16 v[46:49], v[104:107], v[136:139], v[46:49]
	v_mfma_f32_16x16x32_bf16 v[42:45], v[112:115], v[136:139], v[42:45]
	v_mfma_f32_16x16x32_bf16 v[38:41], v[104:107], v[144:147], v[38:41]
	v_mfma_f32_16x16x32_bf16 v[34:37], v[112:115], v[144:147], v[34:37]
	v_mfma_f32_16x16x32_bf16 v[62:65], v[108:111], v[124:127], v[62:65]
	v_mfma_f32_16x16x32_bf16 v[58:61], v[116:119], v[124:127], v[58:61]
	v_mfma_f32_16x16x32_bf16 v[54:57], v[108:111], v[132:135], v[54:57]
	v_mfma_f32_16x16x32_bf16 v[50:53], v[116:119], v[132:135], v[50:53]
	v_mfma_f32_16x16x32_bf16 v[46:49], v[108:111], v[140:143], v[46:49]
	v_mfma_f32_16x16x32_bf16 v[42:45], v[116:119], v[140:143], v[42:45]
	v_mfma_f32_16x16x32_bf16 v[38:41], v[108:111], v[148:151], v[38:41]
	v_mfma_f32_16x16x32_bf16 v[34:37], v[116:119], v[148:151], v[34:37]
	s_setprio 0
	s_barrier
	v_lshl_add_u64 v[120:121], v[156:157], 0, s[28:29]
	s_add_i32 m0, s1, 0x18000
	global_load_lds_dwordx4 v[120:121], off
	v_lshl_add_u64 v[120:121], v[158:159], 0, s[28:29]
	s_add_i32 m0, s1, 0x1a000
	global_load_lds_dwordx4 v[120:121], off
	v_lshl_add_u64 v[152:153], v[152:153], 0, s[28:29]
	s_add_i32 m0, s1, 0x8000
	s_barrier
	s_waitcnt lgkmcnt(0)
	s_barrier
	ds_read_b128 v[120:123], v0 offset:49152
	ds_read_b128 v[124:127], v0 offset:50176
	ds_read_b128 v[128:131], v0 offset:51200
	ds_read_b128 v[132:135], v0 offset:52224
	ds_read_b128 v[136:139], v0 offset:53248
	ds_read_b128 v[140:143], v0 offset:54272
	ds_read_b128 v[144:147], v0 offset:55296
	ds_read_b128 v[148:151], v0 offset:56320
	global_load_lds_dwordx4 v[152:153], off
	v_lshl_add_u64 v[152:153], v[154:155], 0, s[28:29]
	s_add_i32 m0, s1, 0xa000
	s_nop 0
	global_load_lds_dwordx4 v[152:153], off
	s_barrier
	s_waitcnt lgkmcnt(0)
	s_setprio 1
	s_waitcnt lgkmcnt(0)
	v_mfma_f32_16x16x32_bf16 v[2:5], v[104:107], v[120:123], v[2:5]
	v_mfma_f32_16x16x32_bf16 v[6:9], v[112:115], v[120:123], v[6:9]
	v_mfma_f32_16x16x32_bf16 v[10:13], v[104:107], v[128:131], v[10:13]
	v_mfma_f32_16x16x32_bf16 v[14:17], v[112:115], v[128:131], v[14:17]
	v_mfma_f32_16x16x32_bf16 v[18:21], v[104:107], v[136:139], v[18:21]
	v_mfma_f32_16x16x32_bf16 v[22:25], v[112:115], v[136:139], v[22:25]
	v_mfma_f32_16x16x32_bf16 v[26:29], v[104:107], v[144:147], v[26:29]
	v_mfma_f32_16x16x32_bf16 v[30:33], v[112:115], v[144:147], v[30:33]
	v_mfma_f32_16x16x32_bf16 v[2:5], v[108:111], v[124:127], v[2:5]
	v_mfma_f32_16x16x32_bf16 v[6:9], v[116:119], v[124:127], v[6:9]
	v_mfma_f32_16x16x32_bf16 v[10:13], v[108:111], v[132:135], v[10:13]
	v_mfma_f32_16x16x32_bf16 v[14:17], v[116:119], v[132:135], v[14:17]
	v_mfma_f32_16x16x32_bf16 v[18:21], v[108:111], v[140:143], v[18:21]
	v_mfma_f32_16x16x32_bf16 v[22:25], v[116:119], v[140:143], v[22:25]
	v_mfma_f32_16x16x32_bf16 v[26:29], v[108:111], v[148:151], v[26:29]
	v_mfma_f32_16x16x32_bf16 v[30:33], v[116:119], v[148:151], v[30:33]
	s_setprio 0
	s_barrier
	v_lshl_add_u64 v[104:105], v[160:161], 0, s[28:29]
	s_add_i32 m0, s1, 0x1c000
	global_load_lds_dwordx4 v[104:105], off
	v_lshl_add_u64 v[104:105], v[162:163], 0, s[28:29]
	s_add_i32 m0, s1, 0x1e000
	s_add_i32 s0, s0, 2
	global_load_lds_dwordx4 v[104:105], off
	s_waitcnt vmcnt(6)
	s_add_u32 s10, s10, 0x100
	s_addc_u32 s11, s11, 0
	s_cmp_lt_u32 s0, 28
	s_barrier
	s_barrier
	s_cbranch_scc1 .LBB0_108
	s_add_i32 s1, s1, 0x1e000
	s_mov_b64 s[10:11], 0xf80
	v_readfirstlane_b32 s0, v102
	v_lshl_add_u64 v[68:69], v[68:69], 0, s[10:11]
	s_mov_b32 m0, s0
	v_readfirstlane_b32 s0, v103
	ds_read_b128 v[70:73], v99
	ds_read_b128 v[74:77], v99 offset:1024
	ds_read_b128 v[78:81], v99 offset:2048
	ds_read_b128 v[88:91], v99 offset:3072
	ds_read_b128 v[92:95], v0
	ds_read_b128 v[104:107], v0 offset:1024
	ds_read_b128 v[108:111], v0 offset:2048
	ds_read_b128 v[112:115], v0 offset:3072
	ds_read_b128 v[116:119], v0 offset:4096
	ds_read_b128 v[120:123], v0 offset:5120
	ds_read_b128 v[124:127], v0 offset:6144
	ds_read_b128 v[128:131], v0 offset:7168
	global_load_lds_dwordx4 v[68:69], off
	v_lshl_add_u64 v[66:67], v[66:67], 0, s[10:11]
	s_mov_b32 m0, s0
	s_nop 0
	global_load_lds_dwordx4 v[66:67], off
	s_barrier
	s_waitcnt lgkmcnt(0)
	s_setprio 1
	s_waitcnt lgkmcnt(0)
	v_mfma_f32_16x16x32_bf16 v[62:65], v[70:73], v[92:95], v[62:65]
	v_mfma_f32_16x16x32_bf16 v[58:61], v[78:81], v[92:95], v[58:61]
	v_mfma_f32_16x16x32_bf16 v[54:57], v[70:73], v[108:111], v[54:57]
	v_mfma_f32_16x16x32_bf16 v[50:53], v[78:81], v[108:111], v[50:53]
	v_mfma_f32_16x16x32_bf16 v[46:49], v[70:73], v[116:119], v[46:49]
	v_mfma_f32_16x16x32_bf16 v[42:45], v[78:81], v[116:119], v[42:45]
	v_mfma_f32_16x16x32_bf16 v[38:41], v[70:73], v[124:127], v[38:41]
	v_mfma_f32_16x16x32_bf16 v[34:37], v[78:81], v[124:127], v[34:37]
	v_mfma_f32_16x16x32_bf16 v[62:65], v[74:77], v[104:107], v[62:65]
	v_mfma_f32_16x16x32_bf16 v[58:61], v[88:91], v[104:107], v[58:61]
	v_mfma_f32_16x16x32_bf16 v[54:57], v[74:77], v[112:115], v[54:57]
	v_mfma_f32_16x16x32_bf16 v[50:53], v[88:91], v[112:115], v[50:53]
	v_mfma_f32_16x16x32_bf16 v[46:49], v[74:77], v[120:123], v[46:49]
	v_mfma_f32_16x16x32_bf16 v[42:45], v[88:91], v[120:123], v[42:45]
	v_mfma_f32_16x16x32_bf16 v[38:41], v[74:77], v[128:131], v[38:41]
	v_mfma_f32_16x16x32_bf16 v[34:37], v[88:91], v[128:131], v[34:37]
	s_setprio 0
	s_barrier
	s_barrier
	s_waitcnt lgkmcnt(0)
	s_barrier
	ds_read_b128 v[66:69], v0 offset:16384
	ds_read_b128 v[92:95], v0 offset:17408
	ds_read_b128 v[100:103], v0 offset:18432
	ds_read_b128 v[104:107], v0 offset:19456
	ds_read_b128 v[108:111], v0 offset:20480
	ds_read_b128 v[112:115], v0 offset:21504
	ds_read_b128 v[116:119], v0 offset:22528
	ds_read_b128 v[120:123], v0 offset:23552
	s_waitcnt vmcnt(4)
	s_barrier
	s_waitcnt lgkmcnt(0)
	s_setprio 1
	s_waitcnt lgkmcnt(3)
	v_mfma_f32_16x16x32_bf16 v[18:21], v[70:73], v[108:111], v[18:21]
	v_mfma_f32_16x16x32_bf16 v[2:5], v[70:73], v[66:69], v[2:5]
	v_mfma_f32_16x16x32_bf16 v[6:9], v[78:81], v[66:69], v[6:9]
	s_waitcnt lgkmcnt(2)
	v_mfma_f32_16x16x32_bf16 v[66:69], v[74:77], v[112:115], v[18:21]
	v_mfma_f32_16x16x32_bf16 v[18:21], v[78:81], v[108:111], v[22:25]
	v_mfma_f32_16x16x32_bf16 v[2:5], v[74:77], v[92:95], v[2:5]
	v_mfma_f32_16x16x32_bf16 v[6:9], v[88:91], v[92:95], v[6:9]
	v_mfma_f32_16x16x32_bf16 v[10:13], v[70:73], v[100:103], v[10:13]
	v_mfma_f32_16x16x32_bf16 v[14:17], v[78:81], v[100:103], v[14:17]
	v_mfma_f32_16x16x32_bf16 v[92:95], v[88:91], v[112:115], v[18:21]
	s_waitcnt lgkmcnt(1)
	v_mfma_f32_16x16x32_bf16 v[18:21], v[70:73], v[116:119], v[26:29]
	v_mfma_f32_16x16x32_bf16 v[10:13], v[74:77], v[104:107], v[10:13]
	v_mfma_f32_16x16x32_bf16 v[14:17], v[88:91], v[104:107], v[14:17]
	s_waitcnt lgkmcnt(0)
	v_mfma_f32_16x16x32_bf16 v[70:73], v[74:77], v[120:123], v[18:21]
	v_mfma_f32_16x16x32_bf16 v[18:21], v[78:81], v[116:119], v[30:33]
	v_mfma_f32_16x16x32_bf16 v[74:77], v[88:91], v[120:123], v[18:21]
	s_setprio 0
	s_barrier
	ds_read_b128 v[78:81], v99 offset:32768
	ds_read_b128 v[88:91], v99 offset:33792
	ds_read_b128 v[100:103], v99 offset:34816
	ds_read_b128 v[96:99], v99 offset:35840
	s_nop 0
	ds_read_b128 v[18:21], v0 offset:32768
	ds_read_b128 v[22:25], v0 offset:33792
	ds_read_b128 v[26:29], v0 offset:34816
	ds_read_b128 v[30:33], v0 offset:35840
	ds_read_b128 v[104:107], v0 offset:36864
	ds_read_b128 v[108:111], v0 offset:37888
	ds_read_b128 v[112:115], v0 offset:38912
	ds_read_b128 v[116:119], v0 offset:39936
	s_waitcnt vmcnt(2)
	s_barrier
	s_waitcnt lgkmcnt(0)
	s_setprio 1
	s_waitcnt lgkmcnt(7)
	v_mfma_f32_16x16x32_bf16 v[62:65], v[78:81], v[18:21], v[62:65]
	v_mfma_f32_16x16x32_bf16 v[18:21], v[100:103], v[18:21], v[58:61]
	s_waitcnt lgkmcnt(6)
	v_mfma_f32_16x16x32_bf16 v[58:61], v[96:99], v[22:25], v[18:21]
	s_waitcnt lgkmcnt(5)
	v_mfma_f32_16x16x32_bf16 v[18:21], v[78:81], v[26:29], v[54:57]
	s_waitcnt lgkmcnt(4)
	v_mfma_f32_16x16x32_bf16 v[54:57], v[88:91], v[30:33], v[18:21]
	v_mfma_f32_16x16x32_bf16 v[18:21], v[100:103], v[26:29], v[50:53]
	v_mfma_f32_16x16x32_bf16 v[50:53], v[96:99], v[30:33], v[18:21]
	s_waitcnt lgkmcnt(3)
	v_mfma_f32_16x16x32_bf16 v[18:21], v[78:81], v[104:107], v[46:49]
	s_waitcnt lgkmcnt(2)
	v_mfma_f32_16x16x32_bf16 v[46:49], v[88:91], v[108:111], v[18:21]
	v_mfma_f32_16x16x32_bf16 v[18:21], v[100:103], v[104:107], v[42:45]
	v_mfma_f32_16x16x32_bf16 v[42:45], v[96:99], v[108:111], v[18:21]
	s_waitcnt lgkmcnt(1)
	v_mfma_f32_16x16x32_bf16 v[18:21], v[78:81], v[112:115], v[38:41]
	s_waitcnt lgkmcnt(0)
	v_mfma_f32_16x16x32_bf16 v[38:41], v[88:91], v[116:119], v[18:21]
	v_mfma_f32_16x16x32_bf16 v[18:21], v[100:103], v[112:115], v[34:37]
	v_mfma_f32_16x16x32_bf16 v[62:65], v[88:91], v[22:25], v[62:65]
	v_mfma_f32_16x16x32_bf16 v[34:37], v[96:99], v[116:119], v[18:21]
	s_setprio 0
	s_barrier
	s_waitcnt vmcnt(0)
	s_barrier
	s_waitcnt lgkmcnt(0)
	s_barrier
	s_nop 1
	ds_read_b128 v[18:21], v0 offset:49152
	ds_read_b128 v[22:25], v0 offset:50176
	ds_read_b128 v[104:107], v0 offset:51200
	ds_read_b128 v[108:111], v0 offset:52224
	ds_read_b128 v[112:115], v0 offset:53248
	ds_read_b128 v[116:119], v0 offset:54272
	ds_read_b128 v[120:123], v0 offset:55296
	ds_read_b128 v[124:127], v0 offset:56320
	s_barrier
	s_waitcnt lgkmcnt(0)
	s_setprio 1
	s_waitcnt lgkmcnt(7)
	v_mfma_f32_16x16x32_bf16 v[2:5], v[78:81], v[18:21], v[2:5]
	s_waitcnt lgkmcnt(6)
	v_mfma_f32_16x16x32_bf16 v[30:33], v[88:91], v[22:25], v[2:5]
	v_mfma_f32_16x16x32_bf16 v[2:5], v[100:103], v[18:21], v[6:9]
	v_mfma_f32_16x16x32_bf16 v[26:29], v[96:99], v[22:25], v[2:5]
	s_waitcnt lgkmcnt(5)
	v_mfma_f32_16x16x32_bf16 v[2:5], v[78:81], v[104:107], v[10:13]
	s_waitcnt lgkmcnt(4)
	v_mfma_f32_16x16x32_bf16 v[22:25], v[88:91], v[108:111], v[2:5]
	v_mfma_f32_16x16x32_bf16 v[2:5], v[100:103], v[104:107], v[14:17]
	v_mfma_f32_16x16x32_bf16 v[18:21], v[96:99], v[108:111], v[2:5]
	s_waitcnt lgkmcnt(3)
	v_mfma_f32_16x16x32_bf16 v[2:5], v[78:81], v[112:115], v[66:69]
	s_waitcnt lgkmcnt(2)
	v_mfma_f32_16x16x32_bf16 v[14:17], v[88:91], v[116:119], v[2:5]
	v_mfma_f32_16x16x32_bf16 v[2:5], v[100:103], v[112:115], v[92:95]
	v_mfma_f32_16x16x32_bf16 v[10:13], v[96:99], v[116:119], v[2:5]
	s_waitcnt lgkmcnt(1)
	v_mfma_f32_16x16x32_bf16 v[2:5], v[78:81], v[120:123], v[70:73]
	s_waitcnt lgkmcnt(0)
	v_mfma_f32_16x16x32_bf16 v[6:9], v[88:91], v[124:127], v[2:5]
	v_mfma_f32_16x16x32_bf16 v[2:5], v[100:103], v[120:123], v[74:77]
	v_mfma_f32_16x16x32_bf16 v[2:5], v[96:99], v[124:127], v[2:5]
	s_setprio 0
	s_movk_i32 s0, 0x100
	v_cmp_gt_u32_e32 vcc, s0, v82
	s_barrier
	s_and_saveexec_b64 s[0:1], vcc
	s_cbranch_execz .LBB0_111
	s_barrier

.LBB0_688:
	s_or_b64 exec, exec, s[14:15]
	v_mov_b32_e32 v67, v1
	v_add_u32_e32 v94, 0x18000, v85
	v_lshl_add_u64 v[10:11], s[0:1], 0, v[0:1]
	v_lshl_add_u64 v[12:13], s[0:1], 0, v[66:67]
	v_lshl_add_u64 v[14:15], s[10:11], 0, v[0:1]
	v_lshl_add_u64 v[16:17], s[10:11], 0, v[66:67]
	s_mov_b64 s[10:11], 0x80
	v_readfirstlane_b32 s1, v94
	v_add_u32_e32 v96, 0x1a000, v85
	v_lshl_add_u64 v[10:11], v[10:11], 0, s[10:11]
	s_mov_b32 m0, s1
	v_readfirstlane_b32 s1, v96
	v_add_u32_e32 v97, 0x8000, v85
	s_waitcnt vmcnt(4)
	s_barrier
	global_load_lds_dwordx4 v[10:11], off
	v_lshl_add_u64 v[10:11], v[12:13], 0, s[10:11]
	s_mov_b32 m0, s1
	v_readfirstlane_b32 s1, v97
	v_add_u32_e32 v98, 0xa000, v85
	global_load_lds_dwordx4 v[10:11], off
	v_lshl_add_u64 v[10:11], v[14:15], 0, s[10:11]
	s_mov_b32 m0, s1
	v_readfirstlane_b32 s1, v98
	v_add_u32_e32 v99, 0x1c000, v85
	v_lshl_add_u64 v[18:19], s[12:13], 0, v[0:1]
	global_load_lds_dwordx4 v[10:11], off
	v_lshl_add_u64 v[10:11], v[16:17], 0, s[10:11]
	s_mov_b32 m0, s1
	v_readfirstlane_b32 s1, v99
	v_add_u32_e32 v100, 0x1e000, v85
	v_lshl_add_u64 v[20:21], s[12:13], 0, v[66:67]
	global_load_lds_dwordx4 v[10:11], off
	v_lshl_add_u64 v[10:11], v[18:19], 0, s[10:11]
	s_mov_b32 m0, s1
	v_readfirstlane_b32 s1, v100
	global_load_lds_dwordx4 v[10:11], off
	v_lshl_add_u64 v[10:11], v[20:21], 0, s[10:11]
	s_mov_b32 m0, s1
	s_sub_i32 s10, s62, s54
	global_load_lds_dwordx4 v[10:11], off
	s_sub_i32 s10, s10, s64
	s_sext_i32_i16 s10, s10
	s_lshl_b32 s1, s63, 10
	s_lshl_b32 s10, s10, 8
	s_movk_i32 s14, 0x1600
	s_and_b32 s0, s52, 0x80
	s_add_i32 s1, s1, s10
	v_lshrrev_b32_e32 v10, 1, v2
	v_mul_lo_u32 v2, v4, s14
	s_mov_b32 s11, 0x16000
	s_or_b32 s12, s0, s1
	v_mad_u64_u32 v[10:11], s[0:1], v10, s11, v[2:3]
	s_mul_i32 s13, s12, 0x2c00
	v_or_b32_e32 v2, v10, v3
	s_mul_hi_i32 s10, s12, 0x2c00
	v_add_lshl_u32 v2, v2, v5, 1
	s_add_u32 s0, s16, s13
	v_lshrrev_b32_e32 v5, 1, v6
	v_mul_lo_u32 v4, v8, s14
	s_addc_u32 s1, s17, s10
	v_mad_u64_u32 v[4:5], s[10:11], v5, s11, v[4:5]
	v_or_b32_e32 v4, v4, v7
	v_mov_b32_e32 v3, v1
	v_add_lshl_u32 v4, v4, v9, 1
	v_mov_b32_e32 v5, v1
	v_lshl_add_u64 v[68:69], s[0:1], 0, v[2:3]
	v_lshl_add_u64 v[70:71], s[0:1], 0, v[4:5]
	s_add_u32 s0, s20, s66
	s_addc_u32 s1, s21, s72
	s_addk_i32 s12, 0x80
	s_add_i32 s13, s13, 0x160000
	v_and_b32_e32 v84, 15, v80
	v_bfe_u32 v83, v80, 4, 2
	v_lshlrev_b32_e32 v24, 2, v80
	v_lshl_add_u64 v[72:73], s[0:1], 0, v[2:3]
	v_lshl_add_u64 v[74:75], s[0:1], 0, v[4:5]
	s_mul_hi_i32 s1, s12, 0x2c00
	s_add_u32 s0, s16, s13
	v_bfe_u32 v82, v80, 6, 2
	v_lshlrev_b32_e32 v22, 6, v84
	v_lshlrev_b32_e32 v23, 4, v83
	v_and_b32_e32 v24, 32, v24
	s_waitcnt vmcnt(6)
	s_addc_u32 s1, s17, s1
	v_bitop3_b32 v22, v23, v24, v22 bitop3:0x36
	v_lshlrev_b32_e32 v23, 13, v81
	v_lshl_or_b32 v24, v82, 12, v212
	v_lshl_add_u64 v[76:77], s[0:1], 0, v[2:3]
	v_mov_b32_e32 v2, 0
	v_lshl_add_u64 v[78:79], s[0:1], 0, v[4:5]
	s_mov_b32 s0, -2
	s_mov_b64 s[10:11], 0
	v_add_u32_e32 v95, v24, v22
	v_add_u32_e32 v93, v23, v22
	v_mov_b32_e32 v3, v2
	v_mov_b32_e32 v4, v2
	v_mov_b32_e32 v5, v2
	v_mov_b32_e32 v6, v2
	v_mov_b32_e32 v7, v2
	v_mov_b32_e32 v8, v2
	v_mov_b32_e32 v9, v2
	v_mov_b32_e32 v10, v2
	v_mov_b32_e32 v11, v2
	v_mov_b32_e32 v12, v2
	v_mov_b32_e32 v13, v2
	v_mov_b32_e32 v14, v2
	v_mov_b32_e32 v15, v2
	v_mov_b32_e32 v16, v2
	v_mov_b32_e32 v17, v2
	v_mov_b32_e32 v18, v2
	v_mov_b32_e32 v19, v2
	v_mov_b32_e32 v20, v2
	v_mov_b32_e32 v21, v2
	v_mov_b32_e32 v22, v2
	v_mov_b32_e32 v23, v2
	v_mov_b32_e32 v24, v2
	v_mov_b32_e32 v25, v2
	v_mov_b32_e32 v26, v2
	v_mov_b32_e32 v27, v2
	v_mov_b32_e32 v28, v2
	v_mov_b32_e32 v29, v2
	v_mov_b32_e32 v34, v2
	v_mov_b32_e32 v35, v2
	v_mov_b32_e32 v36, v2
	v_mov_b32_e32 v37, v2
	v_mov_b32_e32 v38, v2
	v_mov_b32_e32 v39, v2
	v_mov_b32_e32 v40, v2
	v_mov_b32_e32 v41, v2
	v_mov_b32_e32 v42, v2
	v_mov_b32_e32 v43, v2
	v_mov_b32_e32 v44, v2
	v_mov_b32_e32 v45, v2
	v_mov_b32_e32 v46, v2
	v_mov_b32_e32 v47, v2
	v_mov_b32_e32 v48, v2
	v_mov_b32_e32 v49, v2
	v_mov_b32_e32 v50, v2
	v_mov_b32_e32 v51, v2
	v_mov_b32_e32 v52, v2
	v_mov_b32_e32 v53, v2
	v_mov_b32_e32 v54, v2
	v_mov_b32_e32 v55, v2
	v_mov_b32_e32 v56, v2
	v_mov_b32_e32 v57, v2
	v_mov_b32_e32 v58, v2
	v_mov_b32_e32 v59, v2
	v_mov_b32_e32 v60, v2
	v_mov_b32_e32 v61, v2
	v_mov_b32_e32 v62, v2
	v_mov_b32_e32 v63, v2
	v_mov_b32_e32 v64, v2
	v_mov_b32_e32 v65, v2
	v_mov_b32_e32 v30, v2
	v_mov_b32_e32 v31, v2
	v_mov_b32_e32 v32, v2
	v_mov_b32_e32 v33, v2
	s_barrier
	v_readfirstlane_b32 s1, v85
	s_nop 1
.LBB0_689:
	ds_read_b128 v[104:107], v95
	ds_read_b128 v[108:111], v95 offset:1024
	ds_read_b128 v[112:115], v95 offset:2048
	ds_read_b128 v[116:119], v95 offset:3072
	v_add_u32_e32 v101, 0xc000, v85
	v_lshl_add_u64 v[152:153], v[72:73], 0, s[10:11]
	v_lshl_add_u64 v[102:103], v[152:153], 0, s[34:35]
	s_add_i32 m0, s1, 0xc000
	ds_read_b128 v[120:123], v93
	ds_read_b128 v[124:127], v93 offset:1024
	ds_read_b128 v[128:131], v93 offset:2048
	ds_read_b128 v[132:135], v93 offset:3072
	ds_read_b128 v[136:139], v93 offset:4096
	ds_read_b128 v[140:143], v93 offset:5120
	ds_read_b128 v[144:147], v93 offset:6144
	ds_read_b128 v[148:151], v93 offset:7168
	global_load_lds_dwordx4 v[102:103], off
	v_add_u32_e32 v102, 0xe000, v85
	v_lshl_add_u64 v[154:155], v[74:75], 0, s[10:11]
	v_lshl_add_u64 v[156:157], v[154:155], 0, s[34:35]
	s_add_i32 m0, s1, 0xe000
	s_nop 0
	global_load_lds_dwordx4 v[156:157], off
	s_waitcnt lgkmcnt(8)
	s_barrier
	s_waitcnt lgkmcnt(0)
	s_setprio 1
	s_waitcnt lgkmcnt(0)
	v_mfma_f32_16x16x32_bf16 v[62:65], v[104:107], v[120:123], v[62:65]
	v_mfma_f32_16x16x32_bf16 v[58:61], v[112:115], v[120:123], v[58:61]
	v_mfma_f32_16x16x32_bf16 v[54:57], v[104:107], v[128:131], v[54:57]
	v_mfma_f32_16x16x32_bf16 v[50:53], v[112:115], v[128:131], v[50:53]
	v_mfma_f32_16x16x32_bf16 v[46:49], v[104:107], v[136:139], v[46:49]
	v_mfma_f32_16x16x32_bf16 v[42:45], v[112:115], v[136:139], v[42:45]
	v_mfma_f32_16x16x32_bf16 v[38:41], v[104:107], v[144:147], v[38:41]
	v_mfma_f32_16x16x32_bf16 v[34:37], v[112:115], v[144:147], v[34:37]
	v_mfma_f32_16x16x32_bf16 v[62:65], v[108:111], v[124:127], v[62:65]
	v_mfma_f32_16x16x32_bf16 v[58:61], v[116:119], v[124:127], v[58:61]
	v_mfma_f32_16x16x32_bf16 v[54:57], v[108:111], v[132:135], v[54:57]
	v_mfma_f32_16x16x32_bf16 v[50:53], v[116:119], v[132:135], v[50:53]
	v_mfma_f32_16x16x32_bf16 v[46:49], v[108:111], v[140:143], v[46:49]
	v_mfma_f32_16x16x32_bf16 v[42:45], v[116:119], v[140:143], v[42:45]
	v_mfma_f32_16x16x32_bf16 v[38:41], v[108:111], v[148:151], v[38:41]
	v_mfma_f32_16x16x32_bf16 v[34:37], v[116:119], v[148:151], v[34:37]
	s_setprio 0
	s_barrier
	v_lshl_add_u64 v[156:157], v[68:69], 0, s[10:11]
	v_lshl_add_u64 v[120:121], v[156:157], 0, s[74:75]
	s_add_i32 m0, s1, 0x10000
	v_lshl_add_u64 v[158:159], v[70:71], 0, s[10:11]
	global_load_lds_dwordx4 v[120:121], off
	v_lshl_add_u64 v[120:121], v[158:159], 0, s[74:75]
	s_add_i32 m0, s1, 0x12000
	global_load_lds_dwordx4 v[120:121], off
	v_lshl_add_u64 v[160:161], v[152:153], 0, s[74:75]
	s_mov_b32 m0, s1
	s_barrier
	s_waitcnt lgkmcnt(0)
	s_barrier
	ds_read_b128 v[120:123], v93 offset:16384
	ds_read_b128 v[124:127], v93 offset:17408
	ds_read_b128 v[128:131], v93 offset:18432
	ds_read_b128 v[132:135], v93 offset:19456
	ds_read_b128 v[136:139], v93 offset:20480
	ds_read_b128 v[140:143], v93 offset:21504
	ds_read_b128 v[144:147], v93 offset:22528
	ds_read_b128 v[148:151], v93 offset:23552
	global_load_lds_dwordx4 v[160:161], off
	v_lshl_add_u64 v[160:161], v[154:155], 0, s[74:75]
	s_add_i32 m0, s1, 0x2000
	s_nop 0
	global_load_lds_dwordx4 v[160:161], off
	s_barrier
	s_waitcnt lgkmcnt(0)
	s_setprio 1
	s_waitcnt lgkmcnt(0)
	v_mfma_f32_16x16x32_bf16 v[2:5], v[104:107], v[120:123], v[2:5]
	v_mfma_f32_16x16x32_bf16 v[6:9], v[112:115], v[120:123], v[6:9]
	v_mfma_f32_16x16x32_bf16 v[10:13], v[104:107], v[128:131], v[10:13]
	v_mfma_f32_16x16x32_bf16 v[14:17], v[112:115], v[128:131], v[14:17]
	v_mfma_f32_16x16x32_bf16 v[18:21], v[104:107], v[136:139], v[18:21]
	v_mfma_f32_16x16x32_bf16 v[22:25], v[112:115], v[136:139], v[22:25]
	v_mfma_f32_16x16x32_bf16 v[26:29], v[104:107], v[144:147], v[26:29]
	v_mfma_f32_16x16x32_bf16 v[30:33], v[112:115], v[144:147], v[30:33]
	v_mfma_f32_16x16x32_bf16 v[2:5], v[108:111], v[124:127], v[2:5]
	v_mfma_f32_16x16x32_bf16 v[6:9], v[116:119], v[124:127], v[6:9]
	v_mfma_f32_16x16x32_bf16 v[10:13], v[108:111], v[132:135], v[10:13]
	v_mfma_f32_16x16x32_bf16 v[14:17], v[116:119], v[132:135], v[14:17]
	v_mfma_f32_16x16x32_bf16 v[18:21], v[108:111], v[140:143], v[18:21]
	v_mfma_f32_16x16x32_bf16 v[22:25], v[116:119], v[140:143], v[22:25]
	v_mfma_f32_16x16x32_bf16 v[26:29], v[108:111], v[148:151], v[26:29]
	v_mfma_f32_16x16x32_bf16 v[30:33], v[116:119], v[148:151], v[30:33]
	s_setprio 0
	s_barrier
	v_lshl_add_u64 v[160:161], v[76:77], 0, s[10:11]
	v_lshl_add_u64 v[104:105], v[160:161], 0, s[74:75]
	s_add_i32 m0, s1, 0x14000
	v_lshl_add_u64 v[162:163], v[78:79], 0, s[10:11]
	global_load_lds_dwordx4 v[104:105], off
	v_lshl_add_u64 v[104:105], v[162:163], 0, s[74:75]
	s_add_i32 m0, s1, 0x16000
	s_nop 0
	global_load_lds_dwordx4 v[104:105], off
	s_waitcnt vmcnt(6)
	s_barrier
	s_barrier
	ds_read_b128 v[104:107], v95 offset:32768
	ds_read_b128 v[108:111], v95 offset:33792
	ds_read_b128 v[112:115], v95 offset:34816
	ds_read_b128 v[116:119], v95 offset:35840
	v_lshl_add_u64 v[164:165], v[152:153], 0, s[78:79]
	s_add_i32 m0, s1, 0x4000
	ds_read_b128 v[120:123], v93 offset:32768
	ds_read_b128 v[124:127], v93 offset:33792
	ds_read_b128 v[128:131], v93 offset:34816
	ds_read_b128 v[132:135], v93 offset:35840
	ds_read_b128 v[136:139], v93 offset:36864
	ds_read_b128 v[140:143], v93 offset:37888
	ds_read_b128 v[144:147], v93 offset:38912
	ds_read_b128 v[148:151], v93 offset:39936
	global_load_lds_dwordx4 v[164:165], off
	v_lshl_add_u64 v[164:165], v[154:155], 0, s[78:79]
	s_add_i32 m0, s1, 0x6000
	s_nop 0
	global_load_lds_dwordx4 v[164:165], off
	s_waitcnt lgkmcnt(8)
	s_barrier
	s_waitcnt lgkmcnt(0)
	s_setprio 1
	s_waitcnt lgkmcnt(0)
	v_mfma_f32_16x16x32_bf16 v[62:65], v[104:107], v[120:123], v[62:65]
	v_mfma_f32_16x16x32_bf16 v[58:61], v[112:115], v[120:123], v[58:61]
	v_mfma_f32_16x16x32_bf16 v[54:57], v[104:107], v[128:131], v[54:57]
	v_mfma_f32_16x16x32_bf16 v[50:53], v[112:115], v[128:131], v[50:53]
	v_mfma_f32_16x16x32_bf16 v[46:49], v[104:107], v[136:139], v[46:49]
	v_mfma_f32_16x16x32_bf16 v[42:45], v[112:115], v[136:139], v[42:45]
	v_mfma_f32_16x16x32_bf16 v[38:41], v[104:107], v[144:147], v[38:41]
	v_mfma_f32_16x16x32_bf16 v[34:37], v[112:115], v[144:147], v[34:37]
	v_mfma_f32_16x16x32_bf16 v[62:65], v[108:111], v[124:127], v[62:65]
	v_mfma_f32_16x16x32_bf16 v[58:61], v[116:119], v[124:127], v[58:61]
	v_mfma_f32_16x16x32_bf16 v[54:57], v[108:111], v[132:135], v[54:57]
	v_mfma_f32_16x16x32_bf16 v[50:53], v[116:119], v[132:135], v[50:53]
	v_mfma_f32_16x16x32_bf16 v[46:49], v[108:111], v[140:143], v[46:49]
	v_mfma_f32_16x16x32_bf16 v[42:45], v[116:119], v[140:143], v[42:45]
	v_mfma_f32_16x16x32_bf16 v[38:41], v[108:111], v[148:151], v[38:41]
	v_mfma_f32_16x16x32_bf16 v[34:37], v[116:119], v[148:151], v[34:37]
	s_setprio 0
	s_barrier
	v_lshl_add_u64 v[120:121], v[156:157], 0, s[28:29]
	s_add_i32 m0, s1, 0x18000
	global_load_lds_dwordx4 v[120:121], off
	v_lshl_add_u64 v[120:121], v[158:159], 0, s[28:29]
	s_add_i32 m0, s1, 0x1a000
	global_load_lds_dwordx4 v[120:121], off
	v_lshl_add_u64 v[152:153], v[152:153], 0, s[28:29]
	s_add_i32 m0, s1, 0x8000
	s_barrier
	s_waitcnt lgkmcnt(0)
	s_barrier
	ds_read_b128 v[120:123], v93 offset:49152
	ds_read_b128 v[124:127], v93 offset:50176
	ds_read_b128 v[128:131], v93 offset:51200
	ds_read_b128 v[132:135], v93 offset:52224
	ds_read_b128 v[136:139], v93 offset:53248
	ds_read_b128 v[140:143], v93 offset:54272
	ds_read_b128 v[144:147], v93 offset:55296
	ds_read_b128 v[148:151], v93 offset:56320
	global_load_lds_dwordx4 v[152:153], off
	v_lshl_add_u64 v[152:153], v[154:155], 0, s[28:29]
	s_add_i32 m0, s1, 0xa000
	s_nop 0
	global_load_lds_dwordx4 v[152:153], off
	s_barrier
	s_waitcnt lgkmcnt(0)
	s_setprio 1
	s_waitcnt lgkmcnt(0)
	v_mfma_f32_16x16x32_bf16 v[2:5], v[104:107], v[120:123], v[2:5]
	v_mfma_f32_16x16x32_bf16 v[6:9], v[112:115], v[120:123], v[6:9]
	v_mfma_f32_16x16x32_bf16 v[10:13], v[104:107], v[128:131], v[10:13]
	v_mfma_f32_16x16x32_bf16 v[14:17], v[112:115], v[128:131], v[14:17]
	v_mfma_f32_16x16x32_bf16 v[18:21], v[104:107], v[136:139], v[18:21]
	v_mfma_f32_16x16x32_bf16 v[22:25], v[112:115], v[136:139], v[22:25]
	v_mfma_f32_16x16x32_bf16 v[26:29], v[104:107], v[144:147], v[26:29]
	v_mfma_f32_16x16x32_bf16 v[30:33], v[112:115], v[144:147], v[30:33]
	v_mfma_f32_16x16x32_bf16 v[2:5], v[108:111], v[124:127], v[2:5]
	v_mfma_f32_16x16x32_bf16 v[6:9], v[116:119], v[124:127], v[6:9]
	v_mfma_f32_16x16x32_bf16 v[10:13], v[108:111], v[132:135], v[10:13]
	v_mfma_f32_16x16x32_bf16 v[14:17], v[116:119], v[132:135], v[14:17]
	v_mfma_f32_16x16x32_bf16 v[18:21], v[108:111], v[140:143], v[18:21]
	v_mfma_f32_16x16x32_bf16 v[22:25], v[116:119], v[140:143], v[22:25]
	v_mfma_f32_16x16x32_bf16 v[26:29], v[108:111], v[148:151], v[26:29]
	v_mfma_f32_16x16x32_bf16 v[30:33], v[116:119], v[148:151], v[30:33]
	s_setprio 0
	s_barrier
	v_lshl_add_u64 v[104:105], v[160:161], 0, s[28:29]
	s_add_i32 m0, s1, 0x1c000
	global_load_lds_dwordx4 v[104:105], off
	v_lshl_add_u64 v[104:105], v[162:163], 0, s[28:29]
	s_add_i32 m0, s1, 0x1e000
	s_add_i32 s0, s0, 2
	global_load_lds_dwordx4 v[104:105], off
	s_waitcnt vmcnt(6)
	s_add_u32 s10, s10, 0x100
	s_addc_u32 s11, s11, 0
	s_cmpk_lt_u32 s0, 0x54
	s_barrier
	s_barrier
	s_cbranch_scc1 .LBB0_689
	s_add_i32 s1, s1, 0x1e000
	s_add_u32 s0, s8, 0x2b80
	s_addc_u32 s1, s9, 0
	v_readfirstlane_b32 s8, v101
	v_lshl_add_u64 v[90:91], s[0:1], 0, v[0:1]
	s_mov_b32 m0, s8
	v_lshl_add_u64 v[66:67], s[0:1], 0, v[66:67]
	v_readfirstlane_b32 s0, v102
	ds_read_b128 v[68:71], v95
	ds_read_b128 v[72:75], v95 offset:1024
	ds_read_b128 v[76:79], v95 offset:2048
	ds_read_b128 v[86:89], v95 offset:3072
	ds_read_b128 v[96:99], v93
	ds_read_b128 v[104:107], v93 offset:1024
	ds_read_b128 v[108:111], v93 offset:2048
	ds_read_b128 v[112:115], v93 offset:3072
	ds_read_b128 v[116:119], v93 offset:4096
	ds_read_b128 v[120:123], v93 offset:5120
	ds_read_b128 v[124:127], v93 offset:6144
	ds_read_b128 v[128:131], v93 offset:7168
	global_load_lds_dwordx4 v[90:91], off
	s_mov_b32 m0, s0
	s_nop 0
	global_load_lds_dwordx4 v[66:67], off
	s_barrier
	s_waitcnt lgkmcnt(0)
	s_setprio 1
	s_waitcnt lgkmcnt(0)
	v_mfma_f32_16x16x32_bf16 v[62:65], v[68:71], v[96:99], v[62:65]
	v_mfma_f32_16x16x32_bf16 v[58:61], v[76:79], v[96:99], v[58:61]
	v_mfma_f32_16x16x32_bf16 v[54:57], v[68:71], v[108:111], v[54:57]
	v_mfma_f32_16x16x32_bf16 v[50:53], v[76:79], v[108:111], v[50:53]
	v_mfma_f32_16x16x32_bf16 v[46:49], v[68:71], v[116:119], v[46:49]
	v_mfma_f32_16x16x32_bf16 v[42:45], v[76:79], v[116:119], v[42:45]
	v_mfma_f32_16x16x32_bf16 v[38:41], v[68:71], v[124:127], v[38:41]
	v_mfma_f32_16x16x32_bf16 v[34:37], v[76:79], v[124:127], v[34:37]
	v_mfma_f32_16x16x32_bf16 v[62:65], v[72:75], v[104:107], v[62:65]
	v_mfma_f32_16x16x32_bf16 v[58:61], v[86:89], v[104:107], v[58:61]
	v_mfma_f32_16x16x32_bf16 v[54:57], v[72:75], v[112:115], v[54:57]
	v_mfma_f32_16x16x32_bf16 v[50:53], v[86:89], v[112:115], v[50:53]
	v_mfma_f32_16x16x32_bf16 v[46:49], v[72:75], v[120:123], v[46:49]
	v_mfma_f32_16x16x32_bf16 v[42:45], v[86:89], v[120:123], v[42:45]
	v_mfma_f32_16x16x32_bf16 v[38:41], v[72:75], v[128:131], v[38:41]
	v_mfma_f32_16x16x32_bf16 v[34:37], v[86:89], v[128:131], v[34:37]
	s_setprio 0
	s_barrier
	s_barrier
	s_waitcnt lgkmcnt(0)
	s_barrier
	ds_read_b128 v[96:99], v93 offset:16384
	ds_read_b128 v[100:103], v93 offset:17408
	ds_read_b128 v[104:107], v93 offset:18432
	ds_read_b128 v[108:111], v93 offset:19456
	ds_read_b128 v[112:115], v93 offset:20480
	ds_read_b128 v[116:119], v93 offset:21504
	ds_read_b128 v[120:123], v93 offset:22528
	ds_read_b128 v[124:127], v93 offset:23552
	s_waitcnt vmcnt(4)
	s_barrier
	s_waitcnt lgkmcnt(0)
	s_setprio 1
	s_waitcnt lgkmcnt(3)
	v_mfma_f32_16x16x32_bf16 v[18:21], v[68:71], v[112:115], v[18:21]
	v_mfma_f32_16x16x32_bf16 v[2:5], v[68:71], v[96:99], v[2:5]
	v_mfma_f32_16x16x32_bf16 v[6:9], v[76:79], v[96:99], v[6:9]
	s_waitcnt lgkmcnt(2)
	v_mfma_f32_16x16x32_bf16 v[96:99], v[72:75], v[116:119], v[18:21]
	v_mfma_f32_16x16x32_bf16 v[18:21], v[76:79], v[112:115], v[22:25]
	v_mfma_f32_16x16x32_bf16 v[2:5], v[72:75], v[100:103], v[2:5]
	v_mfma_f32_16x16x32_bf16 v[6:9], v[86:89], v[100:103], v[6:9]
	v_mfma_f32_16x16x32_bf16 v[10:13], v[68:71], v[104:107], v[10:13]
	v_mfma_f32_16x16x32_bf16 v[14:17], v[76:79], v[104:107], v[14:17]
	v_mfma_f32_16x16x32_bf16 v[100:103], v[86:89], v[116:119], v[18:21]
	s_waitcnt lgkmcnt(1)
	v_mfma_f32_16x16x32_bf16 v[18:21], v[68:71], v[120:123], v[26:29]
	v_mfma_f32_16x16x32_bf16 v[10:13], v[72:75], v[108:111], v[10:13]
	v_mfma_f32_16x16x32_bf16 v[14:17], v[86:89], v[108:111], v[14:17]
	s_waitcnt lgkmcnt(0)
	v_mfma_f32_16x16x32_bf16 v[66:69], v[72:75], v[124:127], v[18:21]
	v_mfma_f32_16x16x32_bf16 v[18:21], v[76:79], v[120:123], v[30:33]
	v_mfma_f32_16x16x32_bf16 v[70:73], v[86:89], v[124:127], v[18:21]
	s_setprio 0
	s_barrier
	ds_read_b128 v[74:77], v95 offset:32768
	ds_read_b128 v[86:89], v95 offset:33792
	ds_read_b128 v[104:107], v95 offset:34816
	ds_read_b128 v[108:111], v95 offset:35840
	s_nop 0
	ds_read_b128 v[18:21], v93 offset:32768
	ds_read_b128 v[22:25], v93 offset:33792
	ds_read_b128 v[26:29], v93 offset:34816
	ds_read_b128 v[30:33], v93 offset:35840
	ds_read_b128 v[112:115], v93 offset:36864
	ds_read_b128 v[116:119], v93 offset:37888
	ds_read_b128 v[120:123], v93 offset:38912
	ds_read_b128 v[124:127], v93 offset:39936
	s_waitcnt vmcnt(2)
	s_barrier
	s_waitcnt lgkmcnt(0)
	s_setprio 1
	s_waitcnt lgkmcnt(7)
	v_mfma_f32_16x16x32_bf16 v[62:65], v[74:77], v[18:21], v[62:65]
	v_mfma_f32_16x16x32_bf16 v[18:21], v[104:107], v[18:21], v[58:61]
	s_waitcnt lgkmcnt(6)
	v_mfma_f32_16x16x32_bf16 v[58:61], v[108:111], v[22:25], v[18:21]
	s_waitcnt lgkmcnt(5)
	v_mfma_f32_16x16x32_bf16 v[18:21], v[74:77], v[26:29], v[54:57]
	s_waitcnt lgkmcnt(4)
	v_mfma_f32_16x16x32_bf16 v[54:57], v[86:89], v[30:33], v[18:21]
	v_mfma_f32_16x16x32_bf16 v[18:21], v[104:107], v[26:29], v[50:53]
	v_mfma_f32_16x16x32_bf16 v[50:53], v[108:111], v[30:33], v[18:21]
	s_waitcnt lgkmcnt(3)
	v_mfma_f32_16x16x32_bf16 v[18:21], v[74:77], v[112:115], v[46:49]
	s_waitcnt lgkmcnt(2)
	v_mfma_f32_16x16x32_bf16 v[46:49], v[86:89], v[116:119], v[18:21]
	v_mfma_f32_16x16x32_bf16 v[18:21], v[104:107], v[112:115], v[42:45]
	v_mfma_f32_16x16x32_bf16 v[42:45], v[108:111], v[116:119], v[18:21]
	s_waitcnt lgkmcnt(1)
	v_mfma_f32_16x16x32_bf16 v[18:21], v[74:77], v[120:123], v[38:41]
	s_waitcnt lgkmcnt(0)
	v_mfma_f32_16x16x32_bf16 v[38:41], v[86:89], v[124:127], v[18:21]
	v_mfma_f32_16x16x32_bf16 v[18:21], v[104:107], v[120:123], v[34:37]
	v_mfma_f32_16x16x32_bf16 v[62:65], v[86:89], v[22:25], v[62:65]
	v_mfma_f32_16x16x32_bf16 v[34:37], v[108:111], v[124:127], v[18:21]
	s_setprio 0
	s_barrier
	s_waitcnt vmcnt(0)
	s_barrier
	s_waitcnt lgkmcnt(0)
	s_barrier
	s_nop 1
	ds_read_b128 v[18:21], v93 offset:49152
	ds_read_b128 v[22:25], v93 offset:50176
	ds_read_b128 v[112:115], v93 offset:51200
	ds_read_b128 v[116:119], v93 offset:52224
	ds_read_b128 v[120:123], v93 offset:53248
	ds_read_b128 v[124:127], v93 offset:54272
	ds_read_b128 v[128:131], v93 offset:55296
	ds_read_b128 v[90:93], v93 offset:56320
	s_barrier
	s_waitcnt lgkmcnt(0)
	s_setprio 1
	s_waitcnt lgkmcnt(7)
	v_mfma_f32_16x16x32_bf16 v[2:5], v[74:77], v[18:21], v[2:5]
	s_waitcnt lgkmcnt(6)
	v_mfma_f32_16x16x32_bf16 v[30:33], v[86:89], v[22:25], v[2:5]
	v_mfma_f32_16x16x32_bf16 v[2:5], v[104:107], v[18:21], v[6:9]
	v_mfma_f32_16x16x32_bf16 v[26:29], v[108:111], v[22:25], v[2:5]
	s_waitcnt lgkmcnt(5)
	v_mfma_f32_16x16x32_bf16 v[2:5], v[74:77], v[112:115], v[10:13]
	s_waitcnt lgkmcnt(4)
	v_mfma_f32_16x16x32_bf16 v[22:25], v[86:89], v[116:119], v[2:5]
	v_mfma_f32_16x16x32_bf16 v[2:5], v[104:107], v[112:115], v[14:17]
	v_mfma_f32_16x16x32_bf16 v[18:21], v[108:111], v[116:119], v[2:5]
	s_waitcnt lgkmcnt(3)
	v_mfma_f32_16x16x32_bf16 v[2:5], v[74:77], v[120:123], v[96:99]
	s_waitcnt lgkmcnt(2)
	v_mfma_f32_16x16x32_bf16 v[14:17], v[86:89], v[124:127], v[2:5]
	v_mfma_f32_16x16x32_bf16 v[2:5], v[104:107], v[120:123], v[100:103]
	v_mfma_f32_16x16x32_bf16 v[10:13], v[108:111], v[124:127], v[2:5]
	s_waitcnt lgkmcnt(1)
	v_mfma_f32_16x16x32_bf16 v[2:5], v[74:77], v[128:131], v[66:69]
	s_waitcnt lgkmcnt(0)
	v_mfma_f32_16x16x32_bf16 v[6:9], v[86:89], v[90:93], v[2:5]
	v_mfma_f32_16x16x32_bf16 v[2:5], v[104:107], v[128:131], v[70:73]
	v_mfma_f32_16x16x32_bf16 v[2:5], v[108:111], v[90:93], v[2:5]
	s_setprio 0
	s_movk_i32 s0, 0x100
	v_cmp_gt_u32_e32 vcc, s0, v80
	s_barrier
	s_and_saveexec_b64 s[0:1], vcc
	s_cbranch_execz .LBB0_692
	s_barrier
